# grid barrier: non-leader workgroups poll the top-level generation word directly instead of the per-XCD word their leader bumps afterwards (one memory round trip less per barrier)
# speedup vs baseline: 1.0367x; 1.0022x over previous
; __device__ __forceinline__ unsigned xb_ld(unsigned* p)              { return __hip_atomic_load(p, __ATOMIC_RELAXED, __HIP_MEMORY_SCOPE_AGENT); }
; __device__ __forceinline__ unsigned xb_add(unsigned* p, unsigned v) { return __hip_atomic_fetch_add(p, v, __ATOMIC_RELAXED, __HIP_MEMORY_SCOPE_AGENT); }
; #define XB_SPIN(cond, bar) do { unsigned _sp = 0; while (cond) { __builtin_amdgcn_s_sleep(1); \
;     if ((++_sp & 255u) == 0u) { if (xb_ld(&(bar)[XB_TMO])) break; if (_sp > XB_SPIN_CAP) { atomicAdd(&(bar)[XB_TMO], 1u); break; } } } } while (0)
; __device__ __forceinline__ void xcd_barrier(const XcdBarrier& b) {
;     ...
;         const unsigned old = xb_add(&bar[XB_XSUB(b.x)], 1u);
;         const unsigned gen = old / nloc;
;         if (old + 1u == (gen + 1u) * nloc) {
;             __builtin_amdgcn_fence(__ATOMIC_RELEASE, "agent");
;             asm volatile("s_waitcnt vmcnt(0)" ::: "memory");
;             const unsigned og = xb_add(&bar[XB_TOP], 1u);
;             const unsigned tg = og / nx;
;             if (og + 1u == (tg + 1u) * nx) xb_add(&bar[XB_TOPGEN], 1u);
;             else XB_SPIN(xb_ld(&bar[XB_TOPGEN]) == tg, bar);
;             __builtin_amdgcn_fence(__ATOMIC_ACQUIRE, "agent");
;             xb_add(&bar[XB_XGEN(b.x)], 1u);
;             asm volatile("s_waitcnt vmcnt(0)" ::: "memory");
;         } else {
;             XB_SPIN(xb_ld(&bar[XB_XGEN(b.x)]) == gen, bar);
;             __builtin_amdgcn_fence(__ATOMIC_ACQUIRE, "agent");
;             asm volatile("s_waitcnt vmcnt(0)" ::: "memory");
;         }
.LBB0_236:
	v_readlane_b32 s2, v251, 53
	s_lshl_b32 s2, s2, 8
	s_add_u32 s2, s88, s2
	s_addc_u32 s3, s89, 0
	v_mov_b32_e32 v0, 0x1000
	v_mov_b32_e32 v3, 1
	global_atomic_add v3, v0, v3, s[2:3] offset:1024 sc0
	v_cvt_f32_u32_e32 v0, v2
	v_sub_u32_e32 v4, 0, v2
	v_rcp_iflag_f32_e32 v0, v0
	s_nop 0
	v_mul_f32_e32 v0, 0x4f7ffffe, v0
	v_cvt_u32_f32_e32 v0, v0
	v_mul_lo_u32 v4, v4, v0
	v_mul_hi_u32 v4, v0, v4
	v_add_u32_e32 v0, v0, v4
	s_waitcnt vmcnt(0)
	v_mul_hi_u32 v0, v3, v0
	v_mul_lo_u32 v4, v0, v2
	v_sub_u32_e32 v4, v3, v4
	v_add_u32_e32 v5, 1, v0
	v_cmp_ge_u32_e32 vcc, v4, v2
	v_add_u32_e32 v3, 1, v3
	s_nop 0
	v_cndmask_b32_e32 v0, v0, v5, vcc
	v_sub_u32_e32 v5, v4, v2
	v_cndmask_b32_e32 v4, v4, v5, vcc
	v_add_u32_e32 v5, 1, v0
	v_cmp_ge_u32_e32 vcc, v4, v2
	s_nop 1
	v_cndmask_b32_e32 v0, v0, v5, vcc
	v_mul_lo_u32 v4, v2, v0
	v_add_u32_e32 v2, v4, v2
	v_cmp_ne_u32_e32 vcc, v3, v2
	s_and_saveexec_b64 s[4:5], vcc
	s_xor_b64 s[4:5], exec, s[4:5]
	s_cbranch_execz .LBB0_250
	s_waitcnt lgkmcnt(0)
	s_add_u32 s12, s68, 0x1ef40500
	s_addc_u32 s13, s69, 0
	v_mov_b32_e32 v1, 0
	global_load_dword v1, v1, s[12:13] sc1
	s_nop 0
	s_waitcnt vmcnt(0)
	v_cmp_eq_u32_e32 vcc, v1, v0
	s_and_saveexec_b64 s[6:7], vcc
	s_cbranch_execz .LBB0_249
	s_add_u32 s10, s68, 0x1ef3d200
	s_addc_u32 s11, s69, 0
	s_mov_b32 s24, 1
	s_mov_b64 s[14:15], 0
	v_mov_b32_e32 v1, 0
	s_branch .LBB0_240

; __device__ __forceinline__ unsigned xb_ld(unsigned* p)              { return __hip_atomic_load(p, __ATOMIC_RELAXED, __HIP_MEMORY_SCOPE_AGENT); }
; __device__ __forceinline__ unsigned xb_add(unsigned* p, unsigned v) { return __hip_atomic_fetch_add(p, v, __ATOMIC_RELAXED, __HIP_MEMORY_SCOPE_AGENT); }
; #define XB_SPIN(cond, bar) do { unsigned _sp = 0; while (cond) { __builtin_amdgcn_s_sleep(1); \
;     if ((++_sp & 255u) == 0u) { if (xb_ld(&(bar)[XB_TMO])) break; if (_sp > XB_SPIN_CAP) { atomicAdd(&(bar)[XB_TMO], 1u); break; } } } } while (0)
; __device__ __forceinline__ void xcd_barrier(const XcdBarrier& b) {
;     ...
;         const unsigned old = xb_add(&bar[XB_XSUB(b.x)], 1u);
;         const unsigned gen = old / nloc;
;         if (old + 1u == (gen + 1u) * nloc) {
;             __builtin_amdgcn_fence(__ATOMIC_RELEASE, "agent");
;             asm volatile("s_waitcnt vmcnt(0)" ::: "memory");
;             const unsigned og = xb_add(&bar[XB_TOP], 1u);
;             const unsigned tg = og / nx;
;             if (og + 1u == (tg + 1u) * nx) xb_add(&bar[XB_TOPGEN], 1u);
;             else XB_SPIN(xb_ld(&bar[XB_TOPGEN]) == tg, bar);
;             __builtin_amdgcn_fence(__ATOMIC_ACQUIRE, "agent");
;             xb_add(&bar[XB_XGEN(b.x)], 1u);
;             asm volatile("s_waitcnt vmcnt(0)" ::: "memory");
;         } else {
;             XB_SPIN(xb_ld(&bar[XB_XGEN(b.x)]) == gen, bar);
;             __builtin_amdgcn_fence(__ATOMIC_ACQUIRE, "agent");
;             asm volatile("s_waitcnt vmcnt(0)" ::: "memory");
;         }
.LBB0_474:
	v_readlane_b32 s2, v251, 53
	s_lshl_b32 s2, s2, 8
	s_add_u32 s2, s88, s2
	s_addc_u32 s3, s89, 0
	v_mov_b32_e32 v0, 0x1000
	v_mov_b32_e32 v3, 1
	global_atomic_add v3, v0, v3, s[2:3] offset:1024 sc0
	v_cvt_f32_u32_e32 v0, v2
	v_sub_u32_e32 v4, 0, v2
	v_rcp_iflag_f32_e32 v0, v0
	s_nop 0
	v_mul_f32_e32 v0, 0x4f7ffffe, v0
	v_cvt_u32_f32_e32 v0, v0
	v_mul_lo_u32 v4, v4, v0
	v_mul_hi_u32 v4, v0, v4
	v_add_u32_e32 v0, v0, v4
	s_waitcnt vmcnt(0)
	v_mul_hi_u32 v0, v3, v0
	v_mul_lo_u32 v4, v0, v2
	v_sub_u32_e32 v4, v3, v4
	v_add_u32_e32 v5, 1, v0
	v_cmp_ge_u32_e32 vcc, v4, v2
	v_add_u32_e32 v3, 1, v3
	s_nop 0
	v_cndmask_b32_e32 v0, v0, v5, vcc
	v_sub_u32_e32 v5, v4, v2
	v_cndmask_b32_e32 v4, v4, v5, vcc
	v_add_u32_e32 v5, 1, v0
	v_cmp_ge_u32_e32 vcc, v4, v2
	s_nop 1
	v_cndmask_b32_e32 v0, v0, v5, vcc
	v_mul_lo_u32 v4, v2, v0
	v_add_u32_e32 v2, v4, v2
	v_cmp_ne_u32_e32 vcc, v3, v2
	s_and_saveexec_b64 s[4:5], vcc
	s_xor_b64 s[4:5], exec, s[4:5]
	s_cbranch_execz .LBB0_488
	s_waitcnt lgkmcnt(0)
	s_add_u32 s10, s68, 0x1ef40500
	s_addc_u32 s11, s69, 0
	v_mov_b32_e32 v1, 0
	global_load_dword v1, v1, s[10:11] sc1
	s_nop 0
	s_waitcnt vmcnt(0)
	v_cmp_eq_u32_e32 vcc, v1, v0
	s_and_saveexec_b64 s[6:7], vcc
	s_cbranch_execz .LBB0_487
	s_add_u32 s8, s68, 0x1ef3d200
	s_addc_u32 s9, s69, 0
	s_mov_b32 s22, 1
	s_mov_b64 s[12:13], 0
	v_mov_b32_e32 v1, 0
	s_branch .LBB0_478
